# v13 + mid-burst s_setprio pair removed so the 32 MFMAs of a phase issue contiguously
# baseline (speedup 1.0000x reference)
; #define PG8_STAGE(bufoff, gbase, voff) do { _Pragma("unroll") for (int _i = 0; _i < 2; ++_i) \
;         __builtin_amdgcn_global_load_lds((const unsigned*)((const char*)(gbase) + (voff)[_i]), (PG8_LAS unsigned*)(lds + (bufoff) + ldsw + _i * 8192), 16, 0, 0); } while (0)
; #define PG8_LDA(dst, b, h) do { _Pragma("unroll") for (int m = 0; m < 4; ++m) _Pragma("unroll") for (int k = 0; k < 2; ++k) dst[m][k] = *(const PG8_LAS bf16x8*)(lds + PG8_SA(b, h) + aoff + m * 2048 + k * 1024); } while (0)
; #define PG8_LDB(dst, b, h) do { _Pragma("unroll") for (int n = 0; n < 2; ++n) _Pragma("unroll") for (int k = 0; k < 2; ++k) dst[n][k] = *(const PG8_LAS bf16x8*)(lds + PG8_SB(b, h) + boff + n * 2048 + k * 1024); } while (0)
; #define PG8_MMA(ai, bj, At, Bt) do { __builtin_amdgcn_s_setprio(1); _Pragma("unroll") for (int m = 0; m < 4; ++m) _Pragma("unroll") for (int n = 0; n < 2; ++n) _Pragma("unroll") for (int k = 0; k < 2; ++k) \
;         acc[ai][bj][m][n] = __builtin_amdgcn_mfma_f32_16x16x32_bf16(Bt[n][k], At[m][k], acc[ai][bj][m][n], 0, 0, 0); __builtin_amdgcn_s_setprio(0); } while (0)
; #define PG8_WAIT_V(n) asm volatile("s_waitcnt vmcnt(" #n ")" ::: "memory")
; #define PG8_WAIT_L(n) asm volatile("s_waitcnt lgkmcnt(" #n ")" ::: "memory")
; #define PG8_BAR __builtin_amdgcn_s_barrier()
; #define PG8_SCHED __builtin_amdgcn_sched_barrier(0)
; template <class Epi, class Sched, bool ALIGN_EPI = false, bool SP2 = false>
; __device__ __forceinline__ void gemm_phase(PG8_LAS unsigned char* lds, const Gemm g, const Sched& S, const Epi& E, const int tid) {
;     ...
;             PG8_LDB(B0, 0, 0); PG8_LDB(B1, 0, 1); PG8_SCHED; PG8_LDA(At, 0, 0); PG8_STAGE(PG8_SA(1, 1), a1 + hstep, voffA);
;             PG8_WAIT_V(8); PG8_WAIT_L(0); PG8_BAR; PG8_MMA(0, 0, At, B0); PG8_MMA(0, 1, At, B1); PG8_BAR; PG8_SCHED;
;             PG8_LDA(At, 0, 1); PG8_STAGE(PG8_SB(0, 0), b2, voffB); PG8_STAGE(PG8_SB(0, 1), b2 + hstep, voffB); PG8_STAGE(PG8_SA(0, 0), a2, voffA);
;             PG8_WAIT_V(8); PG8_WAIT_L(0); PG8_BAR; PG8_MMA(1, 0, At, B0); PG8_MMA(1, 1, At, B1); PG8_BAR; PG8_SCHED;
.LBB0_209:
	s_add_i32 s69, s10, 2
	s_add_u32 s74, s0, 0x80
	s_addc_u32 s11, s1, 0
	s_add_i32 s81, 0, 0x10000
	s_cmp_eq_u32 s39, s10
	s_cselect_b32 s11, s31, s11
	s_cselect_b32 s10, s30, s74
	s_cselect_b32 s77, s35, s13
	s_cselect_b32 s76, s34, s12
	s_add_i32 s74, 0, 0x14000
	v_add_u32_e32 v142, s81, v180
	v_add_u32_e32 v168, s74, v180
	s_waitcnt lgkmcnt(0)
	ds_read_b128 v[130:133], v142
	ds_read_b128 v[134:137], v142 offset:1024
	ds_read_b128 v[138:141], v142 offset:2048
	ds_read_b128 v[142:145], v142 offset:3072
	ds_read_b128 v[164:167], v168
	ds_read_b128 v[184:187], v168 offset:1024
	ds_read_b128 v[188:191], v168 offset:2048
	ds_read_b128 v[200:203], v168 offset:3072
	v_lshl_add_u64 v[168:169], s[0:1], 0, v[160:161]
	s_add_i32 m0, s78, 0xc000
	ds_read_b128 v[204:207], v181
	ds_read_b128 v[208:211], v181 offset:1024
	ds_read_b128 v[212:215], v181 offset:2048
	ds_read_b128 v[216:219], v181 offset:3072
	ds_read_b128 v[220:223], v181 offset:4096
	ds_read_b128 v[226:229], v181 offset:5120
	ds_read_b128 v[238:241], v181 offset:6144
	ds_read_b128 v[242:245], v181 offset:7168
	global_load_lds_dwordx4 v[168:169], off
	v_lshl_add_u64 v[168:169], s[0:1], 0, v[162:163]
	s_add_i32 m0, s78, 0xe000
	s_nop 0
	global_load_lds_dwordx4 v[168:169], off
	s_waitcnt vmcnt(8)
	s_waitcnt lgkmcnt(0)
	s_barrier
	s_setprio 1
	s_waitcnt lgkmcnt(0)
	v_mfma_f32_16x16x32_bf16 v[126:129], v[130:133], v[204:207], v[126:129]
	v_mfma_f32_16x16x32_bf16 v[126:129], v[134:137], v[208:211], v[126:129]
	v_mfma_f32_16x16x32_bf16 v[110:113], v[134:137], v[216:219], v[110:113]
	v_mfma_f32_16x16x32_bf16 v[110:113], v[130:133], v[212:215], v[110:113]
	v_mfma_f32_16x16x32_bf16 v[94:97], v[130:133], v[220:223], v[94:97]
	v_mfma_f32_16x16x32_bf16 v[94:97], v[134:137], v[226:229], v[94:97]
	v_mfma_f32_16x16x32_bf16 v[78:81], v[134:137], v[242:245], v[78:81]
	v_mfma_f32_16x16x32_bf16 v[78:81], v[130:133], v[238:241], v[78:81]
	v_mfma_f32_16x16x32_bf16 v[74:77], v[138:141], v[238:241], v[74:77]
	v_mfma_f32_16x16x32_bf16 v[74:77], v[142:145], v[242:245], v[74:77]
	v_mfma_f32_16x16x32_bf16 v[90:93], v[142:145], v[226:229], v[90:93]
	v_mfma_f32_16x16x32_bf16 v[90:93], v[138:141], v[220:223], v[90:93]
	v_mfma_f32_16x16x32_bf16 v[106:109], v[138:141], v[212:215], v[106:109]
	v_mfma_f32_16x16x32_bf16 v[106:109], v[142:145], v[216:219], v[106:109]
	v_mfma_f32_16x16x32_bf16 v[122:125], v[142:145], v[208:211], v[122:125]
	v_mfma_f32_16x16x32_bf16 v[122:125], v[138:141], v[204:207], v[122:125]
	v_mfma_f32_16x16x32_bf16 v[118:121], v[164:167], v[204:207], v[118:121]
	v_mfma_f32_16x16x32_bf16 v[118:121], v[184:187], v[208:211], v[118:121]
	v_mfma_f32_16x16x32_bf16 v[102:105], v[184:187], v[216:219], v[102:105]
	v_mfma_f32_16x16x32_bf16 v[102:105], v[164:167], v[212:215], v[102:105]
	v_mfma_f32_16x16x32_bf16 v[86:89], v[164:167], v[220:223], v[86:89]
	v_mfma_f32_16x16x32_bf16 v[86:89], v[184:187], v[226:229], v[86:89]
	v_mfma_f32_16x16x32_bf16 v[70:73], v[184:187], v[242:245], v[70:73]
	v_mfma_f32_16x16x32_bf16 v[70:73], v[164:167], v[238:241], v[70:73]
	v_mfma_f32_16x16x32_bf16 v[66:69], v[188:191], v[238:241], v[66:69]
	v_mfma_f32_16x16x32_bf16 v[66:69], v[200:203], v[242:245], v[66:69]
	v_mfma_f32_16x16x32_bf16 v[82:85], v[200:203], v[226:229], v[82:85]
	v_mfma_f32_16x16x32_bf16 v[82:85], v[188:191], v[220:223], v[82:85]
	v_mfma_f32_16x16x32_bf16 v[98:101], v[188:191], v[212:215], v[98:101]
	v_mfma_f32_16x16x32_bf16 v[98:101], v[200:203], v[216:219], v[98:101]
	v_mfma_f32_16x16x32_bf16 v[114:117], v[200:203], v[208:211], v[114:117]
	v_mfma_f32_16x16x32_bf16 v[114:117], v[188:191], v[204:207], v[114:117]
	s_setprio 0
	s_barrier
	s_add_i32 s81, s81, s75
	v_lshl_add_u64 v[168:169], s[76:77], 0, v[148:149]
	s_mov_b32 m0, s81
	ds_read_b128 v[204:207], v181 offset:16384
	ds_read_b128 v[208:211], v181 offset:17408
	ds_read_b128 v[212:215], v181 offset:18432
	ds_read_b128 v[216:219], v181 offset:19456
	ds_read_b128 v[220:223], v181 offset:20480
	ds_read_b128 v[226:229], v181 offset:21504
	ds_read_b128 v[238:241], v181 offset:22528
	ds_read_b128 v[242:245], v181 offset:23552
	global_load_lds_dwordx4 v[168:169], off
	s_add_i32 m0, s81, 0x2000
	v_lshl_add_u64 v[246:247], s[76:77], 0, v[152:153]
	s_add_u32 s76, s76, s82
	s_addc_u32 s77, s77, 0
	s_add_i32 s74, s74, s75
	global_load_lds_dwordx4 v[246:247], off
	v_lshl_add_u64 v[248:249], s[76:77], 0, v[148:149]
	s_mov_b32 m0, s74
	v_lshl_add_u64 v[250:251], s[76:77], 0, v[152:153]
	global_load_lds_dwordx4 v[248:249], off
	s_add_i32 m0, s74, 0x2000
	v_lshl_add_u64 v[252:253], s[10:11], 0, v[146:147]
	global_load_lds_dwordx4 v[250:251], off
	s_mov_b32 m0, s78
	v_lshl_add_u64 v[194:195], s[10:11], 0, v[150:151]
	global_load_lds_dwordx4 v[252:253], off
	s_mov_b32 m0, s79
	s_nop 0
	global_load_lds_dwordx4 v[194:195], off
	s_waitcnt vmcnt(8)
	s_waitcnt lgkmcnt(0)
	s_barrier
; #define PG8_STAGE(bufoff, gbase, voff) do { _Pragma("unroll") for (int _i = 0; _i < 2; ++_i) \
;         __builtin_amdgcn_global_load_lds((const unsigned*)((const char*)(gbase) + (voff)[_i]), (PG8_LAS unsigned*)(lds + (bufoff) + ldsw + _i * 8192), 16, 0, 0); } while (0)
; #define PG8_LDA(dst, b, h) do { _Pragma("unroll") for (int m = 0; m < 4; ++m) _Pragma("unroll") for (int k = 0; k < 2; ++k) dst[m][k] = *(const PG8_LAS bf16x8*)(lds + PG8_SA(b, h) + aoff + m * 2048 + k * 1024); } while (0)
; #define PG8_LDB(dst, b, h) do { _Pragma("unroll") for (int n = 0; n < 2; ++n) _Pragma("unroll") for (int k = 0; k < 2; ++k) dst[n][k] = *(const PG8_LAS bf16x8*)(lds + PG8_SB(b, h) + boff + n * 2048 + k * 1024); } while (0)
; #define PG8_MMA(ai, bj, At, Bt) do { __builtin_amdgcn_s_setprio(1); _Pragma("unroll") for (int m = 0; m < 4; ++m) _Pragma("unroll") for (int n = 0; n < 2; ++n) _Pragma("unroll") for (int k = 0; k < 2; ++k) \
;         acc[ai][bj][m][n] = __builtin_amdgcn_mfma_f32_16x16x32_bf16(Bt[n][k], At[m][k], acc[ai][bj][m][n], 0, 0, 0); __builtin_amdgcn_s_setprio(0); } while (0)
; #define PG8_WAIT_V(n) asm volatile("s_waitcnt vmcnt(" #n ")" ::: "memory")
; #define PG8_WAIT_L(n) asm volatile("s_waitcnt lgkmcnt(" #n ")" ::: "memory")
; #define PG8_BAR __builtin_amdgcn_s_barrier()
; #define PG8_SCHED __builtin_amdgcn_sched_barrier(0)
; template <class Epi, class Sched, bool ALIGN_EPI = false, bool SP2 = false>
; __device__ __forceinline__ void gemm_phase(PG8_LAS unsigned char* lds, const Gemm g, const Sched& S, const Epi& E, const int tid) {
;     ...
;             PG8_WAIT_V(8); PG8_WAIT_L(0); PG8_BAR; PG8_MMA(1, 0, At, B0); PG8_MMA(1, 1, At, B1); PG8_BAR; PG8_SCHED;
;             PG8_LDB(B0, 1, 0); PG8_LDB(B1, 1, 1); PG8_SCHED; PG8_LDA(At, 1, 0); PG8_STAGE(PG8_SA(0, 1), a2 + hstep, voffA);
;             PG8_WAIT_V(8); PG8_WAIT_L(0); PG8_BAR; PG8_MMA(0, 0, At, B0); PG8_MMA(0, 1, At, B1); PG8_BAR; PG8_SCHED;
	s_setprio 1
	s_waitcnt lgkmcnt(0)
	v_mfma_f32_16x16x32_bf16 v[62:65], v[130:133], v[204:207], v[62:65]
	v_mfma_f32_16x16x32_bf16 v[62:65], v[134:137], v[208:211], v[62:65]
	v_mfma_f32_16x16x32_bf16 v[46:49], v[134:137], v[216:219], v[46:49]
	v_mfma_f32_16x16x32_bf16 v[46:49], v[130:133], v[212:215], v[46:49]
	v_mfma_f32_16x16x32_bf16 v[30:33], v[130:133], v[220:223], v[30:33]
	v_mfma_f32_16x16x32_bf16 v[30:33], v[134:137], v[226:229], v[30:33]
	v_mfma_f32_16x16x32_bf16 v[14:17], v[134:137], v[242:245], v[14:17]
	v_mfma_f32_16x16x32_bf16 v[14:17], v[130:133], v[238:241], v[14:17]
	v_mfma_f32_16x16x32_bf16 v[10:13], v[138:141], v[238:241], v[10:13]
	v_mfma_f32_16x16x32_bf16 v[10:13], v[142:145], v[242:245], v[10:13]
	v_mfma_f32_16x16x32_bf16 v[26:29], v[142:145], v[226:229], v[26:29]
	v_mfma_f32_16x16x32_bf16 v[26:29], v[138:141], v[220:223], v[26:29]
	v_mfma_f32_16x16x32_bf16 v[42:45], v[138:141], v[212:215], v[42:45]
	v_mfma_f32_16x16x32_bf16 v[42:45], v[142:145], v[216:219], v[42:45]
	v_mfma_f32_16x16x32_bf16 v[58:61], v[142:145], v[208:211], v[58:61]
	v_mfma_f32_16x16x32_bf16 v[58:61], v[138:141], v[204:207], v[58:61]
	v_mfma_f32_16x16x32_bf16 v[54:57], v[164:167], v[204:207], v[54:57]
	v_mfma_f32_16x16x32_bf16 v[54:57], v[184:187], v[208:211], v[54:57]
	v_mfma_f32_16x16x32_bf16 v[38:41], v[184:187], v[216:219], v[38:41]
	v_mfma_f32_16x16x32_bf16 v[38:41], v[164:167], v[212:215], v[38:41]
	v_mfma_f32_16x16x32_bf16 v[22:25], v[164:167], v[220:223], v[22:25]
	v_mfma_f32_16x16x32_bf16 v[22:25], v[184:187], v[226:229], v[22:25]
	v_mfma_f32_16x16x32_bf16 v[6:9], v[184:187], v[242:245], v[6:9]
	v_mfma_f32_16x16x32_bf16 v[6:9], v[164:167], v[238:241], v[6:9]
	v_mfma_f32_16x16x32_bf16 v[2:5], v[188:191], v[238:241], v[2:5]
	v_mfma_f32_16x16x32_bf16 v[2:5], v[200:203], v[242:245], v[2:5]
	v_mfma_f32_16x16x32_bf16 v[18:21], v[200:203], v[226:229], v[18:21]
	v_mfma_f32_16x16x32_bf16 v[18:21], v[188:191], v[220:223], v[18:21]
	v_mfma_f32_16x16x32_bf16 v[34:37], v[188:191], v[212:215], v[34:37]
	v_mfma_f32_16x16x32_bf16 v[34:37], v[200:203], v[216:219], v[34:37]
	v_mfma_f32_16x16x32_bf16 v[50:53], v[200:203], v[208:211], v[50:53]
	v_mfma_f32_16x16x32_bf16 v[50:53], v[188:191], v[204:207], v[50:53]
	s_setprio 0
	s_barrier
	s_add_i32 s74, 0, 0x18000
	s_add_i32 s76, 0, 0x1c000
	v_add_u32_e32 v142, s74, v180
	v_add_u32_e32 v183, s76, v180
	ds_read_b128 v[130:133], v142
	ds_read_b128 v[134:137], v142 offset:1024
	ds_read_b128 v[138:141], v142 offset:2048
	ds_read_b128 v[142:145], v142 offset:3072
	ds_read_b128 v[164:167], v183
	ds_read_b128 v[184:187], v183 offset:1024
	ds_read_b128 v[188:191], v183 offset:2048
	ds_read_b128 v[200:203], v183 offset:3072
	s_add_u32 s10, s10, s82
	s_addc_u32 s11, s11, 0
	s_mov_b32 m0, s36
	v_lshl_add_u64 v[198:199], s[10:11], 0, v[146:147]
	ds_read_b128 v[204:207], v181 offset:32768
	ds_read_b128 v[208:211], v181 offset:33792
	ds_read_b128 v[212:215], v181 offset:34816
	ds_read_b128 v[216:219], v181 offset:35840
	ds_read_b128 v[220:223], v181 offset:36864
	ds_read_b128 v[226:229], v181 offset:37888
	ds_read_b128 v[238:241], v181 offset:38912
	ds_read_b128 v[242:245], v181 offset:39936
	global_load_lds_dwordx4 v[198:199], off
	v_lshl_add_u64 v[198:199], s[10:11], 0, v[150:151]
	s_mov_b32 m0, s37
	s_nop 0
	global_load_lds_dwordx4 v[198:199], off
	s_waitcnt vmcnt(8)
	s_waitcnt lgkmcnt(0)
	s_barrier
	s_setprio 1
	s_waitcnt lgkmcnt(0)
	v_mfma_f32_16x16x32_bf16 v[126:129], v[130:133], v[204:207], v[126:129]
	v_mfma_f32_16x16x32_bf16 v[126:129], v[134:137], v[208:211], v[126:129]
	v_mfma_f32_16x16x32_bf16 v[110:113], v[134:137], v[216:219], v[110:113]
	v_mfma_f32_16x16x32_bf16 v[110:113], v[130:133], v[212:215], v[110:113]
	v_mfma_f32_16x16x32_bf16 v[94:97], v[130:133], v[220:223], v[94:97]
	v_mfma_f32_16x16x32_bf16 v[94:97], v[134:137], v[226:229], v[94:97]
	v_mfma_f32_16x16x32_bf16 v[78:81], v[134:137], v[242:245], v[78:81]
	v_mfma_f32_16x16x32_bf16 v[78:81], v[130:133], v[238:241], v[78:81]
	v_mfma_f32_16x16x32_bf16 v[74:77], v[138:141], v[238:241], v[74:77]
	v_mfma_f32_16x16x32_bf16 v[74:77], v[142:145], v[242:245], v[74:77]
	v_mfma_f32_16x16x32_bf16 v[90:93], v[142:145], v[226:229], v[90:93]
	v_mfma_f32_16x16x32_bf16 v[90:93], v[138:141], v[220:223], v[90:93]
	v_mfma_f32_16x16x32_bf16 v[106:109], v[138:141], v[212:215], v[106:109]
	v_mfma_f32_16x16x32_bf16 v[106:109], v[142:145], v[216:219], v[106:109]
	v_mfma_f32_16x16x32_bf16 v[122:125], v[142:145], v[208:211], v[122:125]
	v_mfma_f32_16x16x32_bf16 v[122:125], v[138:141], v[204:207], v[122:125]
	v_mfma_f32_16x16x32_bf16 v[118:121], v[164:167], v[204:207], v[118:121]
	v_mfma_f32_16x16x32_bf16 v[118:121], v[184:187], v[208:211], v[118:121]
	v_mfma_f32_16x16x32_bf16 v[102:105], v[184:187], v[216:219], v[102:105]
	v_mfma_f32_16x16x32_bf16 v[102:105], v[164:167], v[212:215], v[102:105]
	v_mfma_f32_16x16x32_bf16 v[86:89], v[164:167], v[220:223], v[86:89]
	v_mfma_f32_16x16x32_bf16 v[86:89], v[184:187], v[226:229], v[86:89]
	v_mfma_f32_16x16x32_bf16 v[70:73], v[184:187], v[242:245], v[70:73]
	v_mfma_f32_16x16x32_bf16 v[70:73], v[164:167], v[238:241], v[70:73]
	v_mfma_f32_16x16x32_bf16 v[66:69], v[188:191], v[238:241], v[66:69]
	v_mfma_f32_16x16x32_bf16 v[66:69], v[200:203], v[242:245], v[66:69]
	v_mfma_f32_16x16x32_bf16 v[82:85], v[200:203], v[226:229], v[82:85]
	v_mfma_f32_16x16x32_bf16 v[82:85], v[188:191], v[220:223], v[82:85]
	v_mfma_f32_16x16x32_bf16 v[98:101], v[188:191], v[212:215], v[98:101]
	v_mfma_f32_16x16x32_bf16 v[98:101], v[200:203], v[216:219], v[98:101]
	v_mfma_f32_16x16x32_bf16 v[114:117], v[200:203], v[208:211], v[114:117]
	v_mfma_f32_16x16x32_bf16 v[114:117], v[188:191], v[204:207], v[114:117]
	s_setprio 0
	s_barrier
; #define PG8_STAGE(bufoff, gbase, voff) do { _Pragma("unroll") for (int _i = 0; _i < 2; ++_i) \
;         __builtin_amdgcn_global_load_lds((const unsigned*)((const char*)(gbase) + (voff)[_i]), (PG8_LAS unsigned*)(lds + (bufoff) + ldsw + _i * 8192), 16, 0, 0); } while (0)
; #define PG8_LDA(dst, b, h) do { _Pragma("unroll") for (int m = 0; m < 4; ++m) _Pragma("unroll") for (int k = 0; k < 2; ++k) dst[m][k] = *(const PG8_LAS bf16x8*)(lds + PG8_SA(b, h) + aoff + m * 2048 + k * 1024); } while (0)
; #define PG8_MMA(ai, bj, At, Bt) do { __builtin_amdgcn_s_setprio(1); _Pragma("unroll") for (int m = 0; m < 4; ++m) _Pragma("unroll") for (int n = 0; n < 2; ++n) _Pragma("unroll") for (int k = 0; k < 2; ++k) \
;         acc[ai][bj][m][n] = __builtin_amdgcn_mfma_f32_16x16x32_bf16(Bt[n][k], At[m][k], acc[ai][bj][m][n], 0, 0, 0); __builtin_amdgcn_s_setprio(0); } while (0)
; #define PG8_WAIT_V(n) asm volatile("s_waitcnt vmcnt(" #n ")" ::: "memory")
; #define PG8_WAIT_L(n) asm volatile("s_waitcnt lgkmcnt(" #n ")" ::: "memory")
; #define PG8_BAR __builtin_amdgcn_s_barrier()
; #define PG8_SCHED __builtin_amdgcn_sched_barrier(0)
; template <class Epi, class Sched, bool ALIGN_EPI = false, bool SP2 = false>
; __device__ __forceinline__ void gemm_phase(PG8_LAS unsigned char* lds, const Gemm g, const Sched& S, const Epi& E, const int tid) {
;     ...
;         for (int t = 0; t < nt; t += 2) {
;             const bool last = (t == nt - 2);
;             const char* a1 = cA + (size_t)(t + 1) * kstep;
;             const char* a2 = last ? nA : cA + (size_t)(t + 2) * kstep; const char* b2 = last ? nB : cB + (size_t)(t + 2) * kstep;
;             const char* a3 = a2 + kstep; const char* b3 = b2 + kstep;
;     ...
;             PG8_LDA(At, 1, 1); PG8_STAGE(PG8_SB(1, 0), b3, voffB); PG8_STAGE(PG8_SB(1, 1), b3 + hstep, voffB); PG8_STAGE(PG8_SA(1, 0), a3, voffA);
;             PG8_WAIT_V(8); PG8_WAIT_L(0); PG8_BAR; PG8_MMA(1, 0, At, B0); PG8_MMA(1, 1, At, B1); PG8_BAR; PG8_SCHED;
;     ...
;         if constexpr (ALIGN_EPI) { if (wr == 0) PG8_BAR; }
;         if constexpr (!Epi::AFTER_DRAIN) { E(acc, cur, wr, wc, fr, fq); S.done(cur); }
	s_add_i32 s10, s74, s75
	v_lshl_add_u64 v[168:169], v[168:169], 0, s[90:91]
	s_mov_b32 m0, s10
	ds_read_b128 v[204:207], v181 offset:49152
	ds_read_b128 v[208:211], v181 offset:50176
	ds_read_b128 v[212:215], v181 offset:51200
	ds_read_b128 v[216:219], v181 offset:52224
	ds_read_b128 v[220:223], v181 offset:53248
	ds_read_b128 v[226:229], v181 offset:54272
	ds_read_b128 v[238:241], v181 offset:55296
	ds_read_b128 v[242:245], v181 offset:56320
	global_load_lds_dwordx4 v[168:169], off
	v_lshl_add_u64 v[168:169], v[246:247], 0, s[90:91]
	s_add_i32 m0, s10, 0x2000
	s_add_i32 s10, s76, s75
	global_load_lds_dwordx4 v[168:169], off
	v_lshl_add_u64 v[168:169], v[248:249], 0, s[90:91]
	s_mov_b32 m0, s10
	s_nop 0
	global_load_lds_dwordx4 v[168:169], off
	v_lshl_add_u64 v[168:169], v[250:251], 0, s[90:91]
	s_add_i32 m0, s10, 0x2000
	s_nop 0
	global_load_lds_dwordx4 v[168:169], off
	v_lshl_add_u64 v[168:169], v[252:253], 0, s[90:91]
	s_mov_b32 m0, s40
	s_nop 0
	global_load_lds_dwordx4 v[168:169], off
	v_lshl_add_u64 v[168:169], v[194:195], 0, s[90:91]
	s_mov_b32 m0, s41
	s_nop 0
	global_load_lds_dwordx4 v[168:169], off
	s_waitcnt vmcnt(8)
	s_waitcnt lgkmcnt(0)
	s_barrier
	s_setprio 1
	s_waitcnt lgkmcnt(0)
	v_mfma_f32_16x16x32_bf16 v[62:65], v[130:133], v[204:207], v[62:65]
	v_mfma_f32_16x16x32_bf16 v[62:65], v[134:137], v[208:211], v[62:65]
	v_mfma_f32_16x16x32_bf16 v[46:49], v[134:137], v[216:219], v[46:49]
	v_mfma_f32_16x16x32_bf16 v[46:49], v[130:133], v[212:215], v[46:49]
	v_mfma_f32_16x16x32_bf16 v[30:33], v[130:133], v[220:223], v[30:33]
	v_mfma_f32_16x16x32_bf16 v[30:33], v[134:137], v[226:229], v[30:33]
	v_mfma_f32_16x16x32_bf16 v[14:17], v[134:137], v[242:245], v[14:17]
	v_mfma_f32_16x16x32_bf16 v[14:17], v[130:133], v[238:241], v[14:17]
	v_mfma_f32_16x16x32_bf16 v[10:13], v[138:141], v[238:241], v[10:13]
	v_mfma_f32_16x16x32_bf16 v[10:13], v[142:145], v[242:245], v[10:13]
	v_mfma_f32_16x16x32_bf16 v[26:29], v[142:145], v[226:229], v[26:29]
	v_mfma_f32_16x16x32_bf16 v[26:29], v[138:141], v[220:223], v[26:29]
	v_mfma_f32_16x16x32_bf16 v[42:45], v[138:141], v[212:215], v[42:45]
	v_mfma_f32_16x16x32_bf16 v[42:45], v[142:145], v[216:219], v[42:45]
	v_mfma_f32_16x16x32_bf16 v[58:61], v[142:145], v[208:211], v[58:61]
	v_mfma_f32_16x16x32_bf16 v[58:61], v[138:141], v[204:207], v[58:61]
	v_mfma_f32_16x16x32_bf16 v[54:57], v[164:167], v[204:207], v[54:57]
	v_mfma_f32_16x16x32_bf16 v[54:57], v[184:187], v[208:211], v[54:57]
	v_mfma_f32_16x16x32_bf16 v[38:41], v[184:187], v[216:219], v[38:41]
	v_mfma_f32_16x16x32_bf16 v[38:41], v[164:167], v[212:215], v[38:41]
	v_mfma_f32_16x16x32_bf16 v[22:25], v[164:167], v[220:223], v[22:25]
	v_mfma_f32_16x16x32_bf16 v[22:25], v[184:187], v[226:229], v[22:25]
	v_mfma_f32_16x16x32_bf16 v[6:9], v[184:187], v[242:245], v[6:9]
	v_mfma_f32_16x16x32_bf16 v[6:9], v[164:167], v[238:241], v[6:9]
	v_mfma_f32_16x16x32_bf16 v[2:5], v[188:191], v[238:241], v[2:5]
	v_mfma_f32_16x16x32_bf16 v[2:5], v[200:203], v[242:245], v[2:5]
	v_mfma_f32_16x16x32_bf16 v[18:21], v[200:203], v[226:229], v[18:21]
	v_mfma_f32_16x16x32_bf16 v[18:21], v[188:191], v[220:223], v[18:21]
	v_mfma_f32_16x16x32_bf16 v[34:37], v[188:191], v[212:215], v[34:37]
	v_mfma_f32_16x16x32_bf16 v[34:37], v[200:203], v[216:219], v[34:37]
	v_mfma_f32_16x16x32_bf16 v[50:53], v[200:203], v[208:211], v[50:53]
	v_mfma_f32_16x16x32_bf16 v[50:53], v[188:191], v[204:207], v[50:53]
	s_setprio 0
	s_barrier
	s_add_u32 s0, s0, 0x100
	s_addc_u32 s1, s1, 0
	s_add_u32 s12, s12, 0x100
	s_addc_u32 s13, s13, 0
	s_cmp_ge_u32 s69, s84
	s_mov_b32 s10, s69
	s_cbranch_scc0 .LBB0_209
	s_and_b64 vcc, exec, s[22:23]
	s_cbranch_vccz .LBB0_213
	s_barrier
	s_cmp_lt_i32 s3, 3
	s_mov_b64 s[0:1], -1
	s_cbranch_scc0 .LBB0_214
